# v27 + GEMM prologue issues all 14 first-tile loads before its first wait (vmcnt(2) -> vmcnt(8) after the second batch)
# baseline (speedup 1.0000x reference)
; #define PG8_STAGE(bufoff, gbase, voff) do { _Pragma("unroll") for (int _i = 0; _i < 2; ++_i) \
;         __builtin_amdgcn_global_load_lds((const unsigned*)((const char*)(gbase) + (voff)[_i]), (PG8_LAS unsigned*)(lds + (bufoff) + ldsw + _i * 8192), 16, 0, 0); } while (0)
; #define PG8_WAIT_V(n) asm volatile("s_waitcnt vmcnt(" #n ")" ::: "memory")
; #define PG8_BAR __builtin_amdgcn_s_barrier()
; template <class Epi, class Sched, bool ALIGN_EPI = false, bool SP2 = false>
; __device__ __forceinline__ void gemm_phase(PG8_LAS unsigned char* lds, const Gemm g, const Sched& S, const Epi& E, int tid_in) {
;     ...
;     for (int i = 0; i < 2; ++i) { int R, C; stage_rc(tid * 16 + i * 8192, R, C); const int Rb = Epi::PERM ? ((R & ~31) + perm32(R & 31)) : R;
;         voffA[i] = (unsigned)(R * K + C) * 2u; voffB[i] = (unsigned)(Rb * K + C) * 2u; }
;     const size_t kstep = (size_t)(BK * 2);
;     const size_t hstep = (size_t)HALF * K * 2;
;     const size_t tstep = 2 * hstep;
;     const unsigned ldsw = (unsigned)wid * 1024u;
;     const int aoff = lds_byte(wr * 64 + fr, fq * 8), boff = lds_byte(wc * 32 + fr, fq * 8);
;     ...
;         PG8_STAGE(PG8_SB(0, 0), cB, voffB); PG8_STAGE(PG8_SB(0, 1), cB + hstep, voffB); PG8_STAGE(PG8_SA(0, 0), cA, voffA); PG8_STAGE(PG8_SA(0, 1), cA + hstep, voffA);
;         if (wr == 1) PG8_BAR;
;         PG8_WAIT_V(2); PG8_BAR;
;         PG8_STAGE(PG8_SB(1, 0), cB + kstep, voffB); PG8_STAGE(PG8_SA(1, 0), cA + kstep, voffA); PG8_STAGE(PG8_SB(1, 1), cB + hstep + kstep, voffB);
;         PG8_WAIT_V(6); PG8_BAR;
.LBB0_152:
	v_readlane_b32 s26, v254, 21
	v_readlane_b32 s27, v254, 22
	s_add_u32 s0, s26, 0x17f00000
	v_writelane_b32 v254, s0, 26
	s_addc_u32 s0, s27, 0
	v_writelane_b32 v254, s0, 28
	v_readlane_b32 s8, v252, 5
	v_readlane_b32 s0, v254, 2
	s_lshl_b32 s0, s0, 10
	s_and_b32 s0, s0, 0xfffff800
	s_lshl_b64 s[24:25], s[0:1], 2
	v_readlane_b32 s14, v252, 11
	v_readlane_b32 s15, v252, 12
	s_add_u32 s64, s14, s24
	s_addc_u32 s65, s15, s25
	v_mov_b32_e32 v149, v80
	s_add_u32 s72, s26, 0x1df00000
	v_lshl_add_u64 v[8:9], s[86:87], 0, v[148:149]
	v_mov_b32_e32 v153, v80
	s_addc_u32 s73, s27, 0
	s_add_i32 s67, s70, 0x18000
	v_lshl_add_u64 v[10:11], s[86:87], 0, v[152:153]
	v_mov_b32_e32 v147, v80
	v_readlane_b32 s21, v252, 18
	v_readlane_b32 s23, v252, 20
	s_and_b32 s0, s7, 3
	v_lshl_add_u64 v[8:9], v[8:9], 0, s[48:49]
	s_mov_b32 m0, s67
	s_add_i32 s91, s70, 0x1a000
	v_lshl_add_u64 v[12:13], s[84:85], 0, v[146:147]
	v_mov_b32_e32 v151, v80
	s_lshl_b32 s21, s29, 13
	s_lshl_b32 s23, s0, 12
	global_load_lds_dwordx4 v[8:9], off
	v_lshl_add_u64 v[8:9], v[10:11], 0, s[48:49]
	s_mov_b32 m0, s91
	s_add_i32 s53, s70, 0x8000
	s_add_i32 s66, s70, 0xa000
	v_lshl_add_u64 v[14:15], s[84:85], 0, v[150:151]
	global_load_lds_dwordx4 v[8:9], off
	v_lshl_add_u64 v[8:9], v[12:13], 0, s[48:49]
	s_mov_b32 m0, s53
	s_add_u32 s24, s86, 0x40080
	global_load_lds_dwordx4 v[8:9], off
	v_lshl_add_u64 v[8:9], v[14:15], 0, s[48:49]
	s_mov_b32 m0, s66
	s_addc_u32 s25, s87, 0
	s_add_i32 s75, s70, 0x1c000
	global_load_lds_dwordx4 v[8:9], off
	v_lshl_add_u64 v[8:9], s[24:25], 0, v[148:149]
	s_mov_b32 m0, s75
	s_add_i32 s74, s70, 0x1e000
	global_load_lds_dwordx4 v[8:9], off
	v_lshl_add_u64 v[8:9], s[24:25], 0, v[152:153]
	s_mov_b32 m0, s74
	v_and_b32_e32 v7, 15, v0
	global_load_lds_dwordx4 v[8:9], off
	s_waitcnt vmcnt(8)
	s_barrier
	v_bfe_u32 v0, v0, 4, 2
	v_lshlrev_b32_e32 v8, 3, v0
	v_lshlrev_b32_e32 v9, 4, v0
	v_cmp_eq_u32_e64 s[36:37], 0, v0
	v_xor_b32_e32 v0, 16, v223
	v_cmp_lt_i32_e32 vcc, v0, v225
	v_lshl_or_b32 v176, s29, 6, v7
	v_lshl_or_b32 v9, v7, 6, v9
	v_cndmask_b32_e32 v0, v223, v0, vcc
	v_lshlrev_b32_e32 v197, 2, v0
	v_xor_b32_e32 v0, 32, v223
	v_cmp_lt_i32_e32 vcc, v0, v225
	v_lshlrev_b32_e32 v7, 2, v7
	v_readlane_b32 s9, v252, 6
	v_cndmask_b32_e32 v0, v223, v0, vcc
	v_lshlrev_b32_e32 v198, 2, v0
	v_lshlrev_b32_e32 v0, 14, v1
	v_and_b32_e32 v0, 0xffff8000, v0
	v_lshl_add_u32 v0, v2, 11, v0
	v_and_b32_e32 v1, 1, v1
	v_lshl_or_b32 v0, v1, 6, v0
	v_lshl_add_u32 v154, v3, 1, v0
	v_lshlrev_b32_e32 v0, 14, v4
	v_and_b32_e32 v10, 32, v7
	s_cmpk_lt_u32 s3, 0x100
	v_and_b32_e32 v0, 0xffff8000, v0
	v_readlane_b32 s10, v252, 7
	v_readlane_b32 s11, v252, 8
	v_readlane_b32 s16, v252, 13
	v_readlane_b32 s17, v252, 14
	v_readlane_b32 s18, v252, 15
	v_readlane_b32 s19, v252, 16
	v_bitop3_b32 v177, v9, s21, v10 bitop3:0xde
	s_waitcnt vmcnt(6)
	s_cselect_b64 s[8:9], -1, 0
	s_lshl_b32 s21, s29, 8
	v_lshl_add_u32 v0, v5, 11, v0
	v_and_b32_e32 v1, 1, v4
	v_readlane_b32 s12, v252, 9
	v_readlane_b32 s13, v252, 10
	v_readlane_b32 s20, v252, 17
	v_writelane_b32 v254, s8, 30
	s_add_i32 s21, s21, 0x20000
	v_lshl_or_b32 v0, v1, 6, v0
	v_readlane_b32 s16, v253, 33
	v_readlane_b32 s10, v253, 38
	v_readlane_b32 s14, v253, 42
	v_bitop3_b32 v194, v9, s23, v10 bitop3:0xde
	v_writelane_b32 v254, s9, 31
	v_lshl_or_b32 v195, s0, 5, v8
	s_mov_b32 s20, 0
	v_or_b32_e32 v196, s21, v7
	v_mov_b32_e32 v155, v80
	v_lshl_add_u32 v156, v6, 1, v0
	v_mov_b32_e32 v157, v80
	s_add_i32 s63, s70, 0xc000
	s_add_i32 s62, s70, 0xe000
	s_mov_b32 s71, 0
	v_readlane_b32 s17, v253, 34
	v_readlane_b32 s18, v253, 35
	v_readlane_b32 s19, v253, 36
	v_readlane_b32 s9, v253, 37
	s_mov_b32 s7, s31
	v_readlane_b32 s11, v253, 39
	v_readlane_b32 s15, v253, 43
	s_movk_i32 s3, 0xc1
	s_mov_b64 s[12:13], s[38:39]
	v_readlane_b32 s22, v252, 19
	s_barrier
	s_branch .LBB0_155

; #define PG8_STAGE(bufoff, gbase, voff) do { _Pragma("unroll") for (int _i = 0; _i < 2; ++_i) \
;         __builtin_amdgcn_global_load_lds((const unsigned*)((const char*)(gbase) + (voff)[_i]), (PG8_LAS unsigned*)(lds + (bufoff) + ldsw + _i * 8192), 16, 0, 0); } while (0)
; #define PG8_WAIT_V(n) asm volatile("s_waitcnt vmcnt(" #n ")" ::: "memory")
; #define PG8_BAR __builtin_amdgcn_s_barrier()
; template <class Epi, class Sched, bool ALIGN_EPI = false, bool SP2 = false>
; __device__ __forceinline__ void gemm_phase(PG8_LAS unsigned char* lds, const Gemm g, const Sched& S, const Epi& E, int tid_in) {
;     ...
;     for (int i = 0; i < 2; ++i) { int R, C; stage_rc(tid * 16 + i * 8192, R, C); const int Rb = Epi::PERM ? ((R & ~31) + perm32(R & 31)) : R;
;         voffA[i] = (unsigned)(R * K + C) * 2u; voffB[i] = (unsigned)(Rb * K + C) * 2u; }
;     const size_t kstep = (size_t)(BK * 2);
;     const size_t hstep = (size_t)HALF * K * 2;
;     const size_t tstep = 2 * hstep;
;     const unsigned ldsw = (unsigned)wid * 1024u;
;     const int aoff = lds_byte(wr * 64 + fr, fq * 8), boff = lds_byte(wc * 32 + fr, fq * 8);
;     ...
;         PG8_STAGE(PG8_SB(0, 0), cB, voffB); PG8_STAGE(PG8_SB(0, 1), cB + hstep, voffB); PG8_STAGE(PG8_SA(0, 0), cA, voffA); PG8_STAGE(PG8_SA(0, 1), cA + hstep, voffA);
;         if (wr == 1) PG8_BAR;
;         PG8_WAIT_V(2); PG8_BAR;
;         PG8_STAGE(PG8_SB(1, 0), cB + kstep, voffB); PG8_STAGE(PG8_SA(1, 0), cA + kstep, voffA); PG8_STAGE(PG8_SB(1, 1), cB + hstep + kstep, voffB);
;         PG8_WAIT_V(6); PG8_BAR;
.LBB0_434:
	v_readlane_b32 s0, v254, 2
	s_lshl_b32 s0, s0, 5
	s_and_b32 s0, s0, 0x7fffffc0
	v_mov_b32_e32 v199, v80
	s_add_u32 s40, s92, 0x100000
	v_lshl_add_u64 v[8:9], s[80:81], 0, v[198:199]
	v_mov_b32_e32 v195, v80
	s_addc_u32 s41, s93, 0
	s_and_b32 s53, s27, 3
	s_add_i32 s27, s57, 0x18000
	v_lshl_add_u64 v[10:11], s[80:81], 0, v[194:195]
	v_mov_b32_e32 v201, v80
	v_lshl_add_u64 v[8:9], v[8:9], 0, s[48:49]
	s_mov_b32 m0, s27
	s_add_i32 s58, s57, 0x1a000
	v_lshl_add_u64 v[12:13], s[78:79], 0, v[200:201]
	v_mov_b32_e32 v197, v80
	s_lshl_b32 s65, s52, 13
	s_lshl_b32 s66, s53, 12
	global_load_lds_dwordx4 v[8:9], off
	v_lshl_add_u64 v[8:9], v[10:11], 0, s[48:49]
	s_mov_b32 m0, s58
	s_add_i32 s59, s57, 0x8000
	s_add_i32 s62, s57, 0xa000
	v_lshl_add_u64 v[14:15], s[78:79], 0, v[196:197]
	global_load_lds_dwordx4 v[8:9], off
	v_lshl_add_u64 v[8:9], v[12:13], 0, s[48:49]
	s_mov_b32 m0, s59
	s_add_u32 s42, s80, 0x40080
	global_load_lds_dwordx4 v[8:9], off
	v_lshl_add_u64 v[8:9], v[14:15], 0, s[48:49]
	s_mov_b32 m0, s62
	s_addc_u32 s43, s81, 0
	s_add_i32 s63, s57, 0x1c000
	global_load_lds_dwordx4 v[8:9], off
	v_lshl_add_u64 v[8:9], s[42:43], 0, v[198:199]
	s_mov_b32 m0, s63
	s_add_i32 s64, s57, 0x1e000
	global_load_lds_dwordx4 v[8:9], off
	v_lshl_add_u64 v[8:9], s[42:43], 0, v[194:195]
	s_mov_b32 m0, s64
	v_and_b32_e32 v7, 15, v1
	global_load_lds_dwordx4 v[8:9], off
	s_waitcnt vmcnt(8)
	s_barrier
	v_bfe_u32 v1, v1, 4, 2
	v_lshlrev_b32_e32 v211, 4, v1
	v_lshl_or_b32 v81, s52, 6, v7
	v_lshlrev_b32_e32 v8, 3, v1
	v_lshl_or_b32 v1, v7, 6, v211
	v_lshlrev_b32_e32 v7, 2, v7
	v_and_b32_e32 v9, 32, v7
	v_bitop3_b32 v247, v1, s65, v9 bitop3:0xde
	v_bitop3_b32 v248, v1, s66, v9 bitop3:0xde
	v_xor_b32_e32 v1, 16, v223
	v_cmp_lt_i32_e32 vcc, v1, v225
	s_cmpk_lt_u32 s37, 0x100
	s_sext_i32_i16 s68, s36
	v_cndmask_b32_e32 v1, v223, v1, vcc
	v_lshlrev_b32_e32 v250, 2, v1
	v_xor_b32_e32 v1, 32, v223
	v_cmp_lt_i32_e32 vcc, v1, v225
	s_waitcnt vmcnt(6)
	s_cselect_b64 s[42:43], -1, 0
	s_lshl_b32 s36, s52, 8
	v_cndmask_b32_e32 v1, v223, v1, vcc
	v_lshlrev_b32_e32 v251, 2, v1
	v_lshlrev_b32_e32 v1, 14, v5
	v_and_b32_e32 v1, 0xffff8000, v1
	v_lshl_add_u32 v1, v4, 11, v1
	v_and_b32_e32 v4, 1, v5
	v_lshl_or_b32 v1, v4, 6, v1
	v_lshl_add_u32 v202, v6, 1, v1
	v_lshlrev_b32_e32 v1, 14, v0
	v_and_b32_e32 v1, 0xffff8000, v1
	v_lshl_add_u32 v1, v2, 11, v1
	v_and_b32_e32 v0, 1, v0
	s_add_i32 s36, s36, 0x20000
	v_lshl_or_b32 v0, v0, 6, v1
	v_or_b32_e32 v249, s36, v7
	v_lshl_or_b32 v217, s53, 6, v8
	v_mov_b32_e32 v203, v80
	v_lshl_add_u32 v204, v3, 1, v0
	v_mov_b32_e32 v205, v80
	s_mov_b32 s69, 0
	s_lshl_b64 s[52:53], s[0:1], 2
	v_lshlrev_b32_e32 v206, 2, v8
	s_mov_b32 s0, 0
	s_barrier
	s_branch .LBB0_437

; #define PG8_STAGE(bufoff, gbase, voff) do { _Pragma("unroll") for (int _i = 0; _i < 2; ++_i) \
;         __builtin_amdgcn_global_load_lds((const unsigned*)((const char*)(gbase) + (voff)[_i]), (PG8_LAS unsigned*)(lds + (bufoff) + ldsw + _i * 8192), 16, 0, 0); } while (0)
; #define PG8_WAIT_V(n) asm volatile("s_waitcnt vmcnt(" #n ")" ::: "memory")
; #define PG8_BAR __builtin_amdgcn_s_barrier()
; template <class Epi, class Sched, bool ALIGN_EPI = false, bool SP2 = false>
; __device__ __forceinline__ void gemm_phase(PG8_LAS unsigned char* lds, const Gemm g, const Sched& S, const Epi& E, int tid_in) {
;     ...
;         PG8_STAGE(PG8_SB(1, 0), cB + kstep, voffB); PG8_STAGE(PG8_SA(1, 0), cA + kstep, voffA); PG8_STAGE(PG8_SB(1, 1), cB + hstep + kstep, voffB);
;         PG8_WAIT_V(6); PG8_BAR;
; __global__ void __launch_bounds__(NTHR, 2) mega_fwd(Params P) {
;     ...
;             const bf16_t* A = kind == 7 ? H : BIG; const bf16_t* Bt = kind == 2 ? (f ? w.f2out : w.f1out) : (kind == 7 ? w.wo : w.sout);
;             const bool lazy = kind == 2 && f == 0 && l > 0, c2 = kind == 2 && f == 1 && l < DEPTH - 1;
;             if (lazy) rowscale_prepass(tab, PC, nullptr, T, D, 0, tid, bid, G, WGM_RES, nullptr, 1);
;             EpiResid E{X, (kind == 2 ? 0.5f : 1.0f) * rs, kind == 2 ? (f ? (c2 ? PC : nullptr) : PA) : PB, tab, lazy ? Q.in[20] + (l - 1) * D : nullptr, c2 ? PB : nullptr, c2 ? Q.in[20] + l * D : nullptr}; run_gemm(lds, A, Bt, T, D, kind == 2 ? FF : D, E, bid, G, tid, WGM_RES, kind == 2 ? 1 : 0); } break;
.LBB0_498:
	v_readlane_b32 s14, v253, 52
	v_readlane_b32 s15, v253, 53
	s_and_b64 s[26:27], s[14:15], s[44:45]
	v_readlane_b32 s38, v254, 2
	s_cmp_lt_i32 s38, 3
	s_cselect_b64 s[36:37], -1, 0
	s_and_b64 s[74:75], s[26:27], s[36:37]
	s_and_b64 s[26:27], s[74:75], exec
	v_readlane_b32 s26, v253, 63
	v_readlane_b32 s14, v253, 55
	v_readlane_b32 s27, v254, 0
	v_readlane_b32 s15, v253, 56
	s_cselect_b32 s0, s27, 0
	s_cselect_b32 s24, s26, 0
	s_and_b64 s[26:27], s[14:15], exec
	v_readlane_b32 s14, v253, 59
	v_readlane_b32 s15, v253, 60
	s_cselect_b32 s24, s14, s24
	s_cselect_b32 s0, s15, s0
	s_and_b64 s[26:27], s[44:45], exec
	v_readlane_b32 s26, v253, 61
	v_readlane_b32 s27, v253, 62
	s_cselect_b32 s77, s0, s27
	s_cselect_b32 s76, s24, s26
	s_lshl_b32 s0, s38, 10
	s_add_i32 s26, s0, 0xfffffc00
	s_ashr_i32 s27, s26, 31
	s_lshl_b64 s[26:27], s[26:27], 2
	s_add_u32 s24, s10, s26
	s_addc_u32 s36, s11, s27
	s_and_b64 s[26:27], s[78:79], exec
	s_cselect_b32 s27, s36, 0
	s_cselect_b32 s26, s24, 0
	s_lshl_b64 s[36:37], s[0:1], 2
	s_add_u32 s0, s10, s36
	s_addc_u32 s24, s11, s37
	s_and_b64 s[36:37], s[74:75], exec
	s_cselect_b32 s38, s0, 0
	s_cselect_b32 s24, s24, 0
	s_add_i32 s64, s57, 0x18000
	v_lshl_add_u64 v[0:1], v[0:1], 0, s[48:49]
	s_mov_b32 m0, s64
	s_add_i32 s65, s57, 0x1a000
	global_load_lds_dwordx4 v[0:1], off
	v_lshl_add_u64 v[0:1], v[2:3], 0, s[48:49]
	s_mov_b32 m0, s65
	s_add_i32 s72, s57, 0x8000
	global_load_lds_dwordx4 v[0:1], off
	v_lshl_add_u64 v[0:1], v[8:9], 0, s[48:49]
	s_mov_b32 m0, s72
	s_add_i32 s73, s57, 0xa000
	global_load_lds_dwordx4 v[0:1], off
	v_lshl_add_u64 v[0:1], v[10:11], 0, s[48:49]
	s_mov_b32 m0, s73
	s_add_i32 s61, s57, 0x1c000
	global_load_lds_dwordx4 v[0:1], off
	v_lshl_add_u64 v[0:1], v[4:5], 0, s[48:49]
	s_mov_b32 m0, s61
	s_add_i32 s62, s57, 0x1e000
	global_load_lds_dwordx4 v[0:1], off
	v_lshl_add_u64 v[0:1], v[6:7], 0, s[48:49]
	s_mov_b32 m0, s62
	s_and_b32 s63, s22, 3
	global_load_lds_dwordx4 v[0:1], off
	s_waitcnt vmcnt(8)
	s_barrier
	v_bfe_u32 v0, v12, 4, 2
	v_and_b32_e32 v1, 15, v12
	v_lshlrev_b32_e32 v3, 4, v0
	v_lshl_or_b32 v81, s23, 6, v1
	v_lshl_or_b32 v3, v1, 6, v3
	v_lshlrev_b32_e32 v1, 2, v1
	s_lshr_b32 s66, s21, 6
	v_lshlrev_b32_e32 v2, 3, v0
	s_lshl_b32 s21, s23, 13
	v_and_b32_e32 v4, 32, v1
	v_cmp_eq_u32_e64 s[36:37], 0, v0
	v_xor_b32_e32 v0, 16, v223
	v_bitop3_b32 v214, v3, s21, v4 bitop3:0xde
	s_lshl_b32 s21, s63, 12
	s_add_i32 s94, s66, -2
	v_cmp_lt_i32_e32 vcc, v0, v225
	s_cmpk_lt_u32 s20, 0x100
	v_bitop3_b32 v215, v3, s21, v4 bitop3:0xde
	v_cndmask_b32_e32 v0, v223, v0, vcc
	s_cselect_b64 s[78:79], -1, 0
	s_lshl_b32 s21, s23, 8
	v_lshlrev_b32_e32 v248, 2, v0
	v_xor_b32_e32 v0, 32, v223
	s_ashr_i32 s67, s30, 31
	s_ashr_i32 s20, s60, 31
	s_add_i32 s21, s21, 0x20000
	v_cmp_lt_i32_e32 vcc, v0, v225
	s_cmp_lg_u64 s[26:27], 0
	s_cselect_b64 s[80:81], -1, 0
	v_cndmask_b32_e32 v0, v223, v0, vcc
	s_cmp_eq_u64 s[26:27], 0
	v_lshlrev_b32_e32 v249, 2, v0
	v_add_u32_e32 v0, v15, v13
	v_or_b32_e32 v247, s21, v1
	s_cselect_b32 s83, s24, s27
	s_cselect_b32 s82, s38, s26
	v_add_lshl_u32 v0, v0, v14, 1
	v_mov_b32_e32 v1, v80
	s_mov_b64 s[14:15], s[44:45]
	s_waitcnt vmcnt(6)
	s_cmp_lg_u64 s[82:83], 0
	v_lshl_add_u64 v[174:175], s[70:71], 0, v[0:1]
	v_add_u32_e32 v0, v18, v16
	v_cndmask_b32_e64 v170, 1.0, 0.5, s[14:15]
	s_cselect_b64 s[84:85], -1, 0
	s_cmp_lg_u64 s[76:77], 0
	v_add_lshl_u32 v0, v0, v17, 1
	s_mov_b32 s0, 0
	v_lshl_or_b32 v216, s63, 5, v2
	v_mov_b32_e32 v172, v170
	v_mov_b32_e32 v173, v170
	s_cselect_b64 s[86:87], -1, 0
	v_lshl_add_u64 v[176:177], s[70:71], 0, v[0:1]
	s_mov_b32 s21, 0
	s_barrier
	s_branch .LBB0_501

; #define PG8_STAGE(bufoff, gbase, voff) do { _Pragma("unroll") for (int _i = 0; _i < 2; ++_i) \
;         __builtin_amdgcn_global_load_lds((const unsigned*)((const char*)(gbase) + (voff)[_i]), (PG8_LAS unsigned*)(lds + (bufoff) + ldsw + _i * 8192), 16, 0, 0); } while (0)
; #define PG8_WAIT_V(n) asm volatile("s_waitcnt vmcnt(" #n ")" ::: "memory")
; #define PG8_BAR __builtin_amdgcn_s_barrier()
; template <class Epi, class Sched, bool ALIGN_EPI = false, bool SP2 = false>
; __device__ __forceinline__ void gemm_phase(PG8_LAS unsigned char* lds, const Gemm g, const Sched& S, const Epi& E, int tid_in) {
;     ...
;     for (int i = 0; i < 2; ++i) { int R, C; stage_rc(tid * 16 + i * 8192, R, C); const int Rb = Epi::PERM ? ((R & ~31) + perm32(R & 31)) : R;
;         voffA[i] = (unsigned)(R * K + C) * 2u; voffB[i] = (unsigned)(Rb * K + C) * 2u; }
;     const size_t kstep = (size_t)(BK * 2);
;     const size_t hstep = (size_t)HALF * K * 2;
;     const size_t tstep = 2 * hstep;
;     const unsigned ldsw = (unsigned)wid * 1024u;
;     const int aoff = lds_byte(wr * 64 + fr, fq * 8), boff = lds_byte(wc * 32 + fr, fq * 8);
;     ...
;         PG8_STAGE(PG8_SB(0, 0), cB, voffB); PG8_STAGE(PG8_SB(0, 1), cB + hstep, voffB); PG8_STAGE(PG8_SA(0, 0), cA, voffA); PG8_STAGE(PG8_SA(0, 1), cA + hstep, voffA);
;         if (wr == 1) PG8_BAR;
;         PG8_WAIT_V(2); PG8_BAR;
;         PG8_STAGE(PG8_SB(1, 0), cB + kstep, voffB); PG8_STAGE(PG8_SA(1, 0), cA + kstep, voffA); PG8_STAGE(PG8_SB(1, 1), cB + hstep + kstep, voffB);
;         PG8_WAIT_V(6); PG8_BAR;
.LBB0_774:
	v_mov_b32_e32 v135, v80
	v_lshl_add_u64 v[8:9], s[70:71], 0, v[134:135]
	v_mov_b32_e32 v131, v80
	s_lshl_b32 s37, s37, 5
	s_add_i32 s58, s22, 0x18000
	v_lshl_add_u64 v[10:11], s[70:71], 0, v[130:131]
	v_mov_b32_e32 v137, v80
	s_and_b32 s37, s37, 0x60
	v_lshl_add_u64 v[8:9], v[8:9], 0, s[48:49]
	s_mov_b32 m0, s58
	s_add_i32 s59, s22, 0x1a000
	v_lshl_add_u64 v[12:13], s[68:69], 0, v[136:137]
	v_mov_b32_e32 v133, v80
	s_lshl_b32 s41, s36, 13
	s_lshl_b32 s44, s37, 7
	global_load_lds_dwordx4 v[8:9], off
	v_lshl_add_u64 v[8:9], v[10:11], 0, s[48:49]
	s_mov_b32 m0, s59
	s_add_i32 s61, s22, 0x8000
	s_add_i32 s62, s22, 0xa000
	v_lshl_add_u64 v[14:15], s[68:69], 0, v[132:133]
	global_load_lds_dwordx4 v[8:9], off
	v_lshl_add_u64 v[8:9], v[12:13], 0, s[48:49]
	s_mov_b32 m0, s61
	s_add_u32 s42, s70, 0x40080
	global_load_lds_dwordx4 v[8:9], off
	v_lshl_add_u64 v[8:9], v[14:15], 0, s[48:49]
	s_mov_b32 m0, s62
	s_addc_u32 s43, s71, 0
	s_add_i32 s63, s22, 0x1c000
	global_load_lds_dwordx4 v[8:9], off
	v_lshl_add_u64 v[8:9], s[42:43], 0, v[134:135]
	s_mov_b32 m0, s63
	s_add_i32 s67, s22, 0x1e000
	global_load_lds_dwordx4 v[8:9], off
	v_lshl_add_u64 v[8:9], s[42:43], 0, v[130:131]
	s_mov_b32 m0, s67
	v_and_b32_e32 v7, 15, v1
	global_load_lds_dwordx4 v[8:9], off
	s_waitcnt vmcnt(8)
	s_barrier
	v_lshrrev_b32_e32 v1, 1, v1
	v_and_b32_e32 v1, 24, v1
	v_lshlrev_b32_e32 v8, 1, v1
	v_or_b32_e32 v147, s37, v1
	v_lshlrev_b32_e32 v1, 14, v5
	v_and_b32_e32 v1, 0xffff8000, v1
	v_lshl_add_u32 v1, v4, 11, v1
	v_and_b32_e32 v4, 1, v5
	v_lshl_or_b32 v1, v4, 6, v1
	v_lshl_or_b32 v81, s36, 6, v7
	v_lshl_or_b32 v8, v7, 6, v8
	v_lshlrev_b32_e32 v7, 2, v7
	v_lshl_add_u32 v138, v6, 1, v1
	v_lshlrev_b32_e32 v1, 14, v0
	v_and_b32_e32 v9, 32, v7
	s_cmpk_lt_u32 s40, 0x100
	v_and_b32_e32 v1, 0xffff8000, v1
	v_bitop3_b32 v144, v8, s41, v9 bitop3:0xde
	s_waitcnt vmcnt(6)
	s_cselect_b64 s[40:41], -1, 0
	s_lshl_b32 s36, s36, 8
	v_lshl_add_u32 v1, v2, 11, v1
	v_and_b32_e32 v0, 1, v0
	s_add_i32 s36, s36, 0x20000
	v_lshl_or_b32 v0, v0, 6, v1
	s_sext_i32_i8 s76, s0
	v_bitop3_b32 v145, v8, s44, v9 bitop3:0xde
	s_ashr_i32 s0, s30, 31
	v_or_b32_e32 v146, s36, v7
	v_mov_b32_e32 v139, v80
	v_lshl_add_u32 v140, v3, 1, v0
	v_mov_b32_e32 v141, v80
	s_mov_b32 s77, 0
	s_mov_b32 s74, 0
	s_barrier
	s_branch .LBB0_777
